# stack13: attention issues the first K-fragment LDS reads right after the tile barrier, ahead of the next tile's global loads and skip test (on top of stack12)
# baseline (speedup 1.0000x reference)
; #define MFMA32(a, b, c) __builtin_amdgcn_mfma_f32_32x32x16_bf16((a), (b), (c), 0, 0, 0)
; DI void attn_unit(const bf16_t* Qb, const bf16_t* Kb, const bf16_t* Vt, bf16_t* MIX, int b, int h, int qb, char* lds, int tid_in) {
;     ...
;         if (t + 1 < NT) gload(t + 1);
;         const int kv0 = t * 128;
;         if (kv0 <= q0 + 32 * wave + 31) {
;             const char* kb_ = lds + buf * ABUF; const char* vb_ = kb_ + AK_BYTES;
;             f32x16 p[4];
;             f32x16 negm;
; #pragma unroll
;             for (int i = 0; i < 16; ++i) negm[i] = -m_run;
; #pragma unroll
;             for (int kb = 0; kb < 4; ++kb) p[kb] = negm;
;             {
;                 bf16x8 kf[2][4];
; #pragma unroll
;                 for (int kb = 0; kb < 4; ++kb) kf[0][kb] = *(const bf16x8*)(kb_ + hh * 2048 + (32 * kb + r) * 16);
; #pragma unroll
;                 for (int ds = 0; ds < 6; ++ds) {
;                     if (ds + 1 < 6) {
; #pragma unroll
;                         for (int kb = 0; kb < 4; ++kb) kf[(ds + 1) & 1][kb] = *(const bf16x8*)(kb_ + (2 * (ds + 1) + hh) * 2048 + (32 * kb + r) * 16); }
;                     __builtin_amdgcn_sched_barrier(0);
;                     __builtin_amdgcn_s_setprio(1);
; #pragma unroll
;                     for (int kb = 0; kb < 4; ++kb) p[kb] = MFMA32(kf[ds & 1][kb], qr[ds], p[kb]);
;                     __builtin_amdgcn_s_setprio(0);
;                     __builtin_amdgcn_sched_barrier(0);
;                 }
;             }
.LBB0_452:
	s_add_i32 s2, s60, -1
	s_and_b32 s78, s2, 1
	s_mul_i32 s2, s78, 0xa400
	s_add_i32 s16, s2, 0
	v_add3_u32 v211, s16, v172, v173
	v_xor_b32_e32 v250, 32, v211
	v_xor_b32_e32 v251, 64, v211
	v_xor_b32_e32 v252, 0x60, v211
	ds_read_b128 v[50:53], v211
	ds_read_b128 v[54:57], v211 offset:512
	ds_read_b128 v[190:193], v211 offset:1024
	ds_read_b128 v[194:197], v211 offset:1536
	ds_read_b128 v[198:201], v250 offset:4096
	ds_read_b128 v[212:215], v250 offset:4608
	ds_read_b128 v[216:219], v250 offset:5120
	ds_read_b128 v[220:223], v250 offset:5632
	s_cmp_lt_u32 s60, s61
	s_cselect_b64 s[52:53], -1, 0
	s_cmp_ge_u32 s60, s61
	s_cbranch_scc1 .LBB0_454
	v_lshl_add_u64 v[34:35], s[28:29], 0, v[152:153]
	v_lshl_add_u64 v[36:37], s[28:29], 0, v[154:155]
	global_load_dwordx4 v[98:101], v[34:35], off
	global_load_dwordx4 v[102:105], v[36:37], off
	v_lshl_add_u64 v[34:35], s[28:29], 0, v[156:157]
	v_lshl_add_u64 v[36:37], s[28:29], 0, v[158:159]
	global_load_dwordx4 v[106:109], v[34:35], off
	global_load_dwordx4 v[110:113], v[36:37], off
	v_lshl_add_u64 v[34:35], s[28:29], 0, v[160:161]
	global_load_dwordx4 v[114:117], v[34:35], off
.LBB0_454:
	v_cmp_le_i32_e32 vcc, s74, v171
	s_and_saveexec_b64 s[54:55], vcc
	s_cbranch_execz .LBB0_468
	v_xor_b32_e32 v34, 0x80000000, v177
	v_mov_b32_e32 v35, v34
	v_mov_b32_e32 v36, v34
	v_mov_b32_e32 v37, v34
	v_mov_b32_e32 v38, v34
	v_mov_b32_e32 v39, v34
	v_mov_b32_e32 v40, v34
	v_mov_b32_e32 v41, v34
	v_mov_b32_e32 v42, v34
	v_mov_b32_e32 v43, v34
	v_mov_b32_e32 v44, v34
	v_mov_b32_e32 v45, v34
	v_mov_b32_e32 v46, v34
	v_mov_b32_e32 v47, v34
	v_mov_b32_e32 v48, v34
	v_mov_b32_e32 v49, v34
	s_setprio 1
	s_waitcnt lgkmcnt(7)
	v_mfma_f32_32x32x16_bf16 v[82:97], v[50:53], v[118:121], v[34:49]
	s_waitcnt lgkmcnt(6)
	v_mfma_f32_32x32x16_bf16 v[66:81], v[54:57], v[118:121], v[34:49]
	s_waitcnt lgkmcnt(5)
	v_mfma_f32_32x32x16_bf16 v[50:65], v[190:193], v[118:121], v[34:49]
	s_waitcnt lgkmcnt(4)
	v_mfma_f32_32x32x16_bf16 v[34:49], v[194:197], v[118:121], v[34:49]
	s_setprio 0
	ds_read_b128 v[190:193], v251 offset:8192
	ds_read_b128 v[194:197], v251 offset:8704
	ds_read_b128 v[224:227], v251 offset:9216
	ds_read_b128 v[228:231], v251 offset:9728
	s_setprio 1
	s_waitcnt lgkmcnt(7)
	v_mfma_f32_32x32x16_bf16 v[82:97], v[198:201], v[122:125], v[82:97]
	s_waitcnt lgkmcnt(6)
	v_mfma_f32_32x32x16_bf16 v[66:81], v[212:215], v[122:125], v[66:81]
	s_waitcnt lgkmcnt(5)
	v_mfma_f32_32x32x16_bf16 v[50:65], v[216:219], v[122:125], v[50:65]
	s_waitcnt lgkmcnt(4)
	v_mfma_f32_32x32x16_bf16 v[34:49], v[220:223], v[122:125], v[34:49]
	s_setprio 0
	ds_read_b128 v[198:201], v252 offset:12288
	ds_read_b128 v[212:215], v252 offset:12800
	ds_read_b128 v[216:219], v252 offset:13312
	ds_read_b128 v[220:223], v252 offset:13824
	s_setprio 1
	s_waitcnt lgkmcnt(7)
	v_mfma_f32_32x32x16_bf16 v[82:97], v[190:193], v[126:129], v[82:97]
	s_waitcnt lgkmcnt(6)
	v_mfma_f32_32x32x16_bf16 v[66:81], v[194:197], v[126:129], v[66:81]
	s_waitcnt lgkmcnt(5)
	v_mfma_f32_32x32x16_bf16 v[50:65], v[224:227], v[126:129], v[50:65]
	s_waitcnt lgkmcnt(4)
	v_mfma_f32_32x32x16_bf16 v[34:49], v[228:231], v[126:129], v[34:49]
	s_setprio 0
	ds_read_b128 v[190:193], v211 offset:16384
	ds_read_b128 v[194:197], v211 offset:16896
	ds_read_b128 v[224:227], v211 offset:17408
	ds_read_b128 v[228:231], v211 offset:17920
	s_setprio 1
	s_waitcnt lgkmcnt(7)
	v_mfma_f32_32x32x16_bf16 v[82:97], v[198:201], v[130:133], v[82:97]
	s_waitcnt lgkmcnt(6)
	v_mfma_f32_32x32x16_bf16 v[66:81], v[212:215], v[130:133], v[66:81]
	s_waitcnt lgkmcnt(5)
	v_mfma_f32_32x32x16_bf16 v[50:65], v[216:219], v[130:133], v[50:65]
	s_waitcnt lgkmcnt(4)
	v_mfma_f32_32x32x16_bf16 v[34:49], v[220:223], v[130:133], v[34:49]
	s_setprio 0
	ds_read_b128 v[198:201], v250 offset:20480
	ds_read_b128 v[212:215], v250 offset:20992
	ds_read_b128 v[216:219], v250 offset:21504
	ds_read_b128 v[220:223], v250 offset:22016
	s_setprio 1
	s_waitcnt lgkmcnt(7)
	v_mfma_f32_32x32x16_bf16 v[82:97], v[190:193], v[134:137], v[82:97]
	s_waitcnt lgkmcnt(6)
	v_mfma_f32_32x32x16_bf16 v[66:81], v[194:197], v[134:137], v[66:81]
	s_waitcnt lgkmcnt(5)
	v_mfma_f32_32x32x16_bf16 v[50:65], v[224:227], v[134:137], v[50:65]
	s_waitcnt lgkmcnt(4)
	v_mfma_f32_32x32x16_bf16 v[34:49], v[228:231], v[134:137], v[34:49]
	s_setprio 0
	s_setprio 1
	s_waitcnt lgkmcnt(3)
	v_mfma_f32_32x32x16_bf16 v[82:97], v[198:201], v[138:141], v[82:97]
	s_waitcnt lgkmcnt(2)
	v_mfma_f32_32x32x16_bf16 v[66:81], v[212:215], v[138:141], v[66:81]
	s_waitcnt lgkmcnt(1)
	v_mfma_f32_32x32x16_bf16 v[50:65], v[216:219], v[138:141], v[50:65]
	s_waitcnt lgkmcnt(0)
	v_mfma_f32_32x32x16_bf16 v[34:49], v[220:223], v[138:141], v[34:49]
	s_setprio 0
	s_add_i32 s2, s74, 0x7f
	v_cmp_gt_i32_e32 vcc, s2, v166
	s_and_saveexec_b64 s[56:57], vcc
	s_cbranch_execz .LBB0_457
; DI int crow(int r, int h) { return (r & 3) + 8 * (r >> 2) + 4 * h; }
; DI void attn_unit(const bf16_t* Qb, const bf16_t* Kb, const bf16_t* Vt, bf16_t* MIX, int b, int h, int qb, char* lds, int tid_in) {
;     ...
;             if (kv0 + 127 > q0 + 32 * wave) {
; #pragma unroll
;                 for (int kb = 0; kb < 4; ++kb)
; #pragma unroll
;                     for (int i = 0; i < 16; ++i) { const int kv = kv0 + 32 * kb + crow(i, hh); if (kv > qabs) p[kb][i] = -1e30f; }
;             }
	v_add_u32_e32 v190, s74, v174
	v_cmp_lt_i32_e32 vcc, v190, v170
	v_add_u32_e32 v191, 2, v190
	s_nop 0
	v_cndmask_b32_e32 v83, v208, v83, vcc
	v_cmp_le_i32_e32 vcc, v190, v170
	s_nop 1
	v_cndmask_b32_e32 v82, v208, v82, vcc
	v_cmp_le_i32_e32 vcc, v191, v170
	v_add_u32_e32 v191, 3, v190
	s_nop 0
	v_cndmask_b32_e32 v84, v208, v84, vcc
	v_cmp_le_i32_e32 vcc, v191, v170
	v_add_u32_e32 v191, 8, v190
	s_nop 0
	v_cndmask_b32_e32 v85, v208, v85, vcc
	v_cmp_le_i32_e32 vcc, v191, v170
	v_add_u32_e32 v191, 9, v190
	s_nop 0
	v_cndmask_b32_e32 v86, v208, v86, vcc
	v_cmp_le_i32_e32 vcc, v191, v170
	v_add_u32_e32 v191, 10, v190
	s_nop 0
	v_cndmask_b32_e32 v87, v208, v87, vcc
	v_cmp_le_i32_e32 vcc, v191, v170
	v_add_u32_e32 v191, 11, v190
	s_nop 0
	v_cndmask_b32_e32 v88, v208, v88, vcc
	v_cmp_le_i32_e32 vcc, v191, v170
	v_add_u32_e32 v191, 16, v190
	s_nop 0
	v_cndmask_b32_e32 v89, v208, v89, vcc
	v_cmp_le_i32_e32 vcc, v191, v170
	v_add_u32_e32 v191, 17, v190
	s_nop 0
	v_cndmask_b32_e32 v90, v208, v90, vcc
	v_cmp_le_i32_e32 vcc, v191, v170
	v_add_u32_e32 v191, 18, v190
	s_nop 0
	v_cndmask_b32_e32 v91, v208, v91, vcc
	v_cmp_le_i32_e32 vcc, v191, v170
	v_add_u32_e32 v191, 19, v190
	s_nop 0
	v_cndmask_b32_e32 v92, v208, v92, vcc
	v_cmp_le_i32_e32 vcc, v191, v170
	v_add_u32_e32 v191, 24, v190
	s_nop 0
	v_cndmask_b32_e32 v93, v208, v93, vcc
	v_cmp_le_i32_e32 vcc, v191, v170
	v_add_u32_e32 v191, 25, v190
	s_nop 0
	v_cndmask_b32_e32 v94, v208, v94, vcc
	v_cmp_le_i32_e32 vcc, v191, v170
	v_add_u32_e32 v191, 26, v190
	s_nop 0
	v_cndmask_b32_e32 v95, v208, v95, vcc
	v_cmp_le_i32_e32 vcc, v191, v170
	v_add_u32_e32 v191, 27, v190
	s_nop 0
	v_cndmask_b32_e32 v96, v208, v96, vcc
	v_cmp_le_i32_e32 vcc, v191, v170
	v_add_u32_e32 v191, 32, v190
	s_nop 0
	v_cndmask_b32_e32 v97, v208, v97, vcc
	v_cmp_lt_i32_e32 vcc, v191, v170
	s_nop 1
	v_cndmask_b32_e32 v67, v208, v67, vcc
	v_cmp_le_i32_e32 vcc, v191, v170
	v_add_u32_e32 v191, 34, v190
	s_nop 0
	v_cndmask_b32_e32 v66, v208, v66, vcc
	v_cmp_le_i32_e32 vcc, v191, v170
	v_add_u32_e32 v191, 35, v190
	s_nop 0
	v_cndmask_b32_e32 v68, v208, v68, vcc
	v_cmp_le_i32_e32 vcc, v191, v170
	v_add_u32_e32 v191, 40, v190
	s_nop 0
	v_cndmask_b32_e32 v69, v208, v69, vcc
	v_cmp_le_i32_e32 vcc, v191, v170
	v_add_u32_e32 v191, 41, v190
	s_nop 0
	v_cndmask_b32_e32 v70, v208, v70, vcc
	v_cmp_le_i32_e32 vcc, v191, v170
	v_add_u32_e32 v191, 42, v190
	s_nop 0
	v_cndmask_b32_e32 v71, v208, v71, vcc
	v_cmp_le_i32_e32 vcc, v191, v170
	v_add_u32_e32 v191, 43, v190
	s_nop 0
	v_cndmask_b32_e32 v72, v208, v72, vcc
	v_cmp_le_i32_e32 vcc, v191, v170
	v_add_u32_e32 v191, 48, v190
	s_nop 0
	v_cndmask_b32_e32 v73, v208, v73, vcc
	v_cmp_le_i32_e32 vcc, v191, v170
	v_add_u32_e32 v191, 49, v190
	s_nop 0
	v_cndmask_b32_e32 v74, v208, v74, vcc
	v_cmp_le_i32_e32 vcc, v191, v170
	v_add_u32_e32 v191, 50, v190
	s_nop 0
	v_cndmask_b32_e32 v75, v208, v75, vcc
	v_cmp_le_i32_e32 vcc, v191, v170
	v_add_u32_e32 v191, 51, v190
	s_nop 0
	v_cndmask_b32_e32 v76, v208, v76, vcc
	v_cmp_le_i32_e32 vcc, v191, v170
	v_add_u32_e32 v191, 56, v190
	s_nop 0
	v_cndmask_b32_e32 v77, v208, v77, vcc
	v_cmp_le_i32_e32 vcc, v191, v170
	v_add_u32_e32 v191, 57, v190
	s_nop 0
	v_cndmask_b32_e32 v78, v208, v78, vcc
	v_cmp_le_i32_e32 vcc, v191, v170
	v_add_u32_e32 v191, 58, v190
	s_nop 0
	v_cndmask_b32_e32 v79, v208, v79, vcc
	v_cmp_le_i32_e32 vcc, v191, v170
	v_add_u32_e32 v191, 59, v190
	s_nop 0
	v_cndmask_b32_e32 v80, v208, v80, vcc
	v_cmp_le_i32_e32 vcc, v191, v170
	v_add_u32_e32 v191, 64, v190
	s_nop 0
	v_cndmask_b32_e32 v81, v208, v81, vcc
; DI int crow(int r, int h) { return (r & 3) + 8 * (r >> 2) + 4 * h; }
; DI void attn_unit(const bf16_t* Qb, const bf16_t* Kb, const bf16_t* Vt, bf16_t* MIX, int b, int h, int qb, char* lds, int tid_in) {
;     ...
;             if (kv0 + 127 > q0 + 32 * wave) {
; #pragma unroll
;                 for (int kb = 0; kb < 4; ++kb)
; #pragma unroll
;                     for (int i = 0; i < 16; ++i) { const int kv = kv0 + 32 * kb + crow(i, hh); if (kv > qabs) p[kb][i] = -1e30f; }
;             }
	v_cmp_lt_i32_e32 vcc, v191, v170
	s_nop 1
	v_cndmask_b32_e32 v51, v208, v51, vcc
	v_cmp_le_i32_e32 vcc, v191, v170
	v_add_u32_e32 v191, 0x42, v190
	s_nop 0
	v_cndmask_b32_e32 v50, v208, v50, vcc
	v_cmp_le_i32_e32 vcc, v191, v170
	v_add_u32_e32 v191, 0x43, v190
	s_nop 0
	v_cndmask_b32_e32 v52, v208, v52, vcc
	v_cmp_le_i32_e32 vcc, v191, v170
	v_add_u32_e32 v191, 0x48, v190
	s_nop 0
	v_cndmask_b32_e32 v53, v208, v53, vcc
	v_cmp_le_i32_e32 vcc, v191, v170
	v_add_u32_e32 v191, 0x49, v190
	s_nop 0
	v_cndmask_b32_e32 v54, v208, v54, vcc
	v_cmp_le_i32_e32 vcc, v191, v170
	v_add_u32_e32 v191, 0x4a, v190
	s_nop 0
	v_cndmask_b32_e32 v55, v208, v55, vcc
	v_cmp_le_i32_e32 vcc, v191, v170
	v_add_u32_e32 v191, 0x4b, v190
	s_nop 0
	v_cndmask_b32_e32 v56, v208, v56, vcc
	v_cmp_le_i32_e32 vcc, v191, v170
	v_add_u32_e32 v191, 0x50, v190
	s_nop 0
	v_cndmask_b32_e32 v57, v208, v57, vcc
	v_cmp_le_i32_e32 vcc, v191, v170
	v_add_u32_e32 v191, 0x51, v190
	s_nop 0
	v_cndmask_b32_e32 v58, v208, v58, vcc
	v_cmp_le_i32_e32 vcc, v191, v170
	v_add_u32_e32 v191, 0x52, v190
	s_nop 0
	v_cndmask_b32_e32 v59, v208, v59, vcc
	v_cmp_le_i32_e32 vcc, v191, v170
	v_add_u32_e32 v191, 0x53, v190
	s_nop 0
	v_cndmask_b32_e32 v60, v208, v60, vcc
	v_cmp_le_i32_e32 vcc, v191, v170
	v_add_u32_e32 v191, 0x58, v190
	s_nop 0
	v_cndmask_b32_e32 v61, v208, v61, vcc
	v_cmp_le_i32_e32 vcc, v191, v170
	v_add_u32_e32 v191, 0x59, v190
	s_nop 0
	v_cndmask_b32_e32 v62, v208, v62, vcc
	v_cmp_le_i32_e32 vcc, v191, v170
	v_add_u32_e32 v191, 0x5a, v190
	s_nop 0
	v_cndmask_b32_e32 v63, v208, v63, vcc
	v_cmp_le_i32_e32 vcc, v191, v170
	v_add_u32_e32 v191, 0x5b, v190
	s_nop 0
	v_cndmask_b32_e32 v64, v208, v64, vcc
	v_cmp_le_i32_e32 vcc, v191, v170
	v_add_u32_e32 v191, 0x60, v190
	s_nop 0
	v_cndmask_b32_e32 v65, v208, v65, vcc
	v_cmp_lt_i32_e32 vcc, v191, v170
	s_nop 1
	v_cndmask_b32_e32 v35, v208, v35, vcc
	v_cmp_le_i32_e32 vcc, v191, v170
	v_add_u32_e32 v191, 0x62, v190
	s_nop 0
	v_cndmask_b32_e32 v34, v208, v34, vcc
	v_cmp_le_i32_e32 vcc, v191, v170
	v_add_u32_e32 v191, 0x63, v190
	s_nop 0
	v_cndmask_b32_e32 v36, v208, v36, vcc
	v_cmp_le_i32_e32 vcc, v191, v170
	v_add_u32_e32 v191, 0x68, v190
	s_nop 0
	v_cndmask_b32_e32 v37, v208, v37, vcc
	v_cmp_le_i32_e32 vcc, v191, v170
	v_add_u32_e32 v191, 0x69, v190
	s_nop 0
	v_cndmask_b32_e32 v38, v208, v38, vcc
	v_cmp_le_i32_e32 vcc, v191, v170
	v_add_u32_e32 v191, 0x6a, v190
	s_nop 0
	v_cndmask_b32_e32 v39, v208, v39, vcc
	v_cmp_le_i32_e32 vcc, v191, v170
	v_add_u32_e32 v191, 0x6b, v190
	s_nop 0
	v_cndmask_b32_e32 v40, v208, v40, vcc
	v_cmp_le_i32_e32 vcc, v191, v170
	v_add_u32_e32 v191, 0x70, v190
	s_nop 0
	v_cndmask_b32_e32 v41, v208, v41, vcc
	v_cmp_le_i32_e32 vcc, v191, v170
	v_add_u32_e32 v191, 0x71, v190
	s_nop 0
	v_cndmask_b32_e32 v42, v208, v42, vcc
	v_cmp_le_i32_e32 vcc, v191, v170
	v_add_u32_e32 v191, 0x72, v190
	s_nop 0
	v_cndmask_b32_e32 v43, v208, v43, vcc
	v_cmp_le_i32_e32 vcc, v191, v170
	v_add_u32_e32 v191, 0x73, v190
	s_nop 0
	v_cndmask_b32_e32 v44, v208, v44, vcc
	v_cmp_le_i32_e32 vcc, v191, v170
	v_add_u32_e32 v191, 0x78, v190
	s_nop 0
	v_cndmask_b32_e32 v45, v208, v45, vcc
	v_cmp_le_i32_e32 vcc, v191, v170
	v_add_u32_e32 v191, 0x79, v190
	s_nop 0
	v_cndmask_b32_e32 v46, v208, v46, vcc
	v_cmp_le_i32_e32 vcc, v191, v170
	v_add_u32_e32 v191, 0x7a, v190
	v_add_u32_e32 v190, 0x7b, v190
	v_cndmask_b32_e32 v47, v208, v47, vcc
	v_cmp_le_i32_e32 vcc, v191, v170
	s_nop 1
	v_cndmask_b32_e32 v48, v208, v48, vcc
	v_cmp_le_i32_e32 vcc, v190, v170
	s_nop 1
	v_cndmask_b32_e32 v49, v208, v49, vcc
